# v52 plus retention tile: query-fragment loads issued right behind the V staging loads (before the staging waits and the barrier)
# speedup vs baseline: 1.0089x; 1.0089x over previous
.LBB0_892:
	s_and_b32 s4, s12, 7
	v_cvt_f32_ubyte0_e32 v0, s4
	v_sub_f32_e32 v36, 0xc0a00000, v0
	s_ashr_i32 s14, s12, 3
	v_cmp_gt_f32_e32 vcc, s19, v36
	v_mov_b32_e32 v217, v208
	s_and_b64 s[0:1], vcc, exec
	s_cselect_b32 s5, 0xffffffc0, 0
	s_lshl_b32 s6, s14, 7
	v_ashrrev_i32_e32 v34, 5, v217
	v_add_u32_e32 v2, s6, v34
	v_mad_i64_i32 v[2:3], s[0:1], v2, s23, v[180:181]
	v_add_u32_e32 v4, 0x200, v217
	v_and_b32_e32 v216, 31, v217
	s_lshl_b32 s0, s4, 9
	s_mov_b32 s1, s7
	v_ashrrev_i32_e32 v38, 5, v4
	v_lshlrev_b32_e32 v0, 4, v216
	v_lshl_add_u64 v[2:3], v[2:3], 0, s[0:1]
	v_add_u32_e32 v4, s6, v38
	v_add_u32_e32 v10, 0x400, v217
	v_lshl_add_u64 v[2:3], v[2:3], 0, v[0:1]
	v_mad_i64_i32 v[4:5], s[2:3], v4, s23, v[180:181]
	v_ashrrev_i32_e32 v39, 5, v10
	v_cndmask_b32_e32 v37, 0, v210, vcc
	v_add_co_u32_e32 v2, vcc, s24, v2
	v_lshl_add_u64 v[4:5], v[4:5], 0, s[0:1]
	v_add_u32_e32 v10, s6, v39
	v_add_u32_e32 v12, 0x600, v217
	v_addc_co_u32_e32 v3, vcc, 0, v3, vcc
	v_lshl_add_u64 v[4:5], v[4:5], 0, v[0:1]
	v_mad_i64_i32 v[10:11], s[2:3], v10, s23, v[180:181]
	v_ashrrev_i32_e32 v40, 5, v12
	v_add_co_u32_e32 v6, vcc, s24, v4
	v_lshl_add_u64 v[10:11], v[10:11], 0, s[0:1]
	v_add_u32_e32 v12, s6, v40
	v_add_u32_e32 v18, 0x800, v217
	v_addc_co_u32_e32 v7, vcc, 0, v5, vcc
	v_lshl_add_u64 v[10:11], v[10:11], 0, v[0:1]
	v_mad_i64_i32 v[12:13], s[2:3], v12, s23, v[180:181]
	v_ashrrev_i32_e32 v41, 5, v18
	v_add_co_u32_e32 v10, vcc, s24, v10
	v_lshl_add_u64 v[12:13], v[12:13], 0, s[0:1]
	v_add_u32_e32 v18, s6, v41
	v_add_u32_e32 v20, 0xa00, v217
	v_addc_co_u32_e32 v11, vcc, 0, v11, vcc
	v_lshl_add_u64 v[12:13], v[12:13], 0, v[0:1]
	v_mad_i64_i32 v[18:19], s[2:3], v18, s23, v[180:181]
	v_ashrrev_i32_e32 v42, 5, v20
	v_add_co_u32_e32 v14, vcc, s24, v12
	v_lshl_add_u64 v[18:19], v[18:19], 0, s[0:1]
	v_add_u32_e32 v20, s6, v42
	v_add_u32_e32 v26, 0xc00, v217
	v_addc_co_u32_e32 v15, vcc, 0, v13, vcc
	v_lshl_add_u64 v[18:19], v[18:19], 0, v[0:1]
	v_mad_i64_i32 v[20:21], s[2:3], v20, s23, v[180:181]
	v_ashrrev_i32_e32 v43, 5, v26
	v_add_co_u32_e32 v18, vcc, s24, v18
	v_lshl_add_u64 v[20:21], v[20:21], 0, s[0:1]
	v_add_u32_e32 v26, s6, v43
	v_add_u32_e32 v30, 0xe00, v217
	v_addc_co_u32_e32 v19, vcc, 0, v19, vcc
	v_lshl_add_u64 v[20:21], v[20:21], 0, v[0:1]
	v_mad_i64_i32 v[26:27], s[2:3], v26, s23, v[180:181]
	v_ashrrev_i32_e32 v44, 5, v30
	global_load_dwordx4 v[2:5], v[2:3], off
	s_nop 0
	global_load_dwordx4 v[6:9], v[6:7], off
	v_add_co_u32_e32 v22, vcc, s24, v20
	v_lshl_add_u64 v[26:27], v[26:27], 0, s[0:1]
	v_add_u32_e32 v30, s6, v44
	v_addc_co_u32_e32 v23, vcc, 0, v21, vcc
	v_lshl_add_u64 v[26:27], v[26:27], 0, v[0:1]
	v_mad_i64_i32 v[30:31], s[2:3], v30, s23, v[180:181]
	global_load_dwordx4 v[10:13], v[10:11], off
	s_nop 0
	global_load_dwordx4 v[14:17], v[14:15], off
	v_add_co_u32_e32 v26, vcc, s24, v26
	v_lshl_add_u64 v[30:31], v[30:31], 0, s[0:1]
	s_nop 0
	v_addc_co_u32_e32 v27, vcc, 0, v27, vcc
	v_lshl_add_u64 v[30:31], v[30:31], 0, v[0:1]
	global_load_dwordx4 v[18:21], v[18:19], off
	s_nop 0
	global_load_dwordx4 v[22:25], v[22:23], off
	v_add_co_u32_e32 v30, vcc, s24, v30
	global_load_dwordx4 v[26:29], v[26:27], off
	s_nop 0
	v_addc_co_u32_e32 v31, vcc, 0, v31, vcc
	global_load_dwordx4 v[30:33], v[30:31], off
	v_add_u32_e32 v0, 0, v0
	v_mad_u64_u32 v[34:35], s[0:1], v34, s25, v[0:1]
	v_bfe_u32 v221, v217, 6, 2
	s_ashr_i32 s15, s14, 31
	v_lshl_or_b32 v81, v221, 5, v216
	s_lshl_b64 s[16:17], s[14:15], 7
	v_or_b32_e32 v218, s16, v81
	v_mad_u64_u32 v[182:183], s[0:1], v218, s23, v[180:181]
	s_lshl_b32 s6, s4, 8
	v_bfe_u32 v80, v217, 5, 1
	v_mad_i32_i24 v183, s17, v214, v183
	v_mov_b32_e32 v219, s17
	s_cmp_gt_i32 s14, 0
	s_mov_b64 s[16:17], -1
	v_lshl_add_u64 v[82:83], v[182:183], 0, s[6:7]
	v_lshlrev_b32_e32 v84, 4, v80
	v_mov_b32_e32 v85, 0
	v_lshl_add_u64 v[82:83], v[82:83], 0, v[84:85]
	global_load_dwordx4 v[96:99], v[82:83], off
	global_load_dwordx4 v[100:103], v[82:83], off offset:32
	global_load_dwordx4 v[104:107], v[82:83], off offset:64
	global_load_dwordx4 v[108:111], v[82:83], off offset:96
	global_load_dwordx4 v[112:115], v[82:83], off offset:128
	global_load_dwordx4 v[116:119], v[82:83], off offset:160
	global_load_dwordx4 v[120:123], v[82:83], off offset:192
	global_load_dwordx4 v[124:127], v[82:83], off offset:224
	s_waitcnt vmcnt(15)
	ds_write_b128 v34, v[2:5]
	v_mad_u64_u32 v[2:3], s[0:1], v38, s25, v[0:1]
	s_waitcnt vmcnt(14)
	ds_write_b128 v2, v[6:9]
	v_mad_u64_u32 v[2:3], s[0:1], v39, s25, v[0:1]
	s_waitcnt vmcnt(13)
	ds_write_b128 v2, v[10:13]
	v_mad_u64_u32 v[2:3], s[0:1], v40, s25, v[0:1]
	s_waitcnt vmcnt(12)
	ds_write_b128 v2, v[14:17]
	v_mad_u64_u32 v[2:3], s[0:1], v41, s25, v[0:1]
	s_waitcnt vmcnt(11)
	ds_write_b128 v2, v[18:21]
	v_mad_u64_u32 v[2:3], s[0:1], v42, s25, v[0:1]
	s_waitcnt vmcnt(10)
	ds_write_b128 v2, v[22:25]
	v_mad_u64_u32 v[2:3], s[0:1], v43, s25, v[0:1]
	s_waitcnt vmcnt(9)
	ds_write_b128 v2, v[26:29]
	v_mad_u64_u32 v[2:3], s[0:1], v44, s25, v[0:1]
	s_waitcnt vmcnt(8)
	ds_write_b128 v2, v[30:33]
	s_waitcnt lgkmcnt(0)
	s_barrier
	v_add_f32_e32 v0, v36, v37
	v_exp_f32_e32 v0, v0
	s_nop 0
	v_ldexp_f32 v0, v0, s5
	v_sub_f32_e32 v2, 1.0, v0
	v_frexp_mant_f32_e32 v3, v2
	v_cmp_gt_f32_e64 s[4:5], s20, v3
	v_cmp_gt_f32_e32 vcc, s22, v0
	v_cmp_nlt_f32_e64 s[0:1], 1.0, v0
	v_cmp_neq_f32_e64 s[2:3], 1.0, v0
	s_cbranch_scc1 .LBB0_894
	s_mov_b64 s[16:17], 0
